# P1 K-loop: LDS-DMA loads in saddr form (SGPR base + 32-bit VGPR offset, next-K-tile via offset:128 with M0 compensated), 64-bit VALU address adds removed
# speedup vs baseline: 1.0147x; 1.0012x over previous
.LBB0_104:
	s_add_i32 s30, s38, 0x44
	s_add_i32 s31, s38, 0xffffffbc
	s_cmp_lt_u32 s31, 8
	s_cselect_b32 s31, s31, s38
	s_cmp_lt_i32 s38, 8
	s_cselect_b32 s38, s30, s31
	s_ashr_i32 s41, s40, 31
	s_lshl_b64 s[30:31], s[40:41], 20
	s_add_u32 s42, s4, s30
	s_addc_u32 s43, s5, s31
	s_and_b64 s[30:31], s[36:37], exec
	s_cselect_b32 s41, s43, s49
	s_cselect_b32 s47, s42, s48
	s_ashr_i32 s39, s38, 31
	s_lshl_b64 s[30:31], s[38:39], 20
	s_add_u32 s44, s6, s30
	s_addc_u32 s45, s7, s31
	s_and_b64 s[30:31], s[36:37], exec
	s_cselect_b32 s39, s45, s1
	s_cselect_b32 s55, s44, s0
	s_add_u32 s60, s0, 0x100
	s_addc_u32 s61, s1, 0
	s_add_u32 s0, s48, 0x80080
	s_addc_u32 s1, s49, 0
	s_mov_b32 s62, -2
	s_add_u32 s30, s0, 0xfff80080
	s_addc_u32 s31, s1, -1
	s_add_i32 s63, 0, 0x10000
	s_cmp_eq_u32 s62, 28
	s_cselect_b32 s51, s41, s31
	s_cselect_b32 s50, s47, s30
	v_add_u32_e32 v150, s63, v153
	s_cselect_b32 s49, s39, s61
	s_cselect_b32 s48, s55, s60
	s_add_i32 s64, 0, 0x14000
	ds_read_b128 v[146:149], v150
	ds_read_b128 v[156:159], v150 offset:1024
	ds_read_b128 v[160:163], v150 offset:2048
	ds_read_b128 v[174:177], v150 offset:3072
	v_add_u32_e32 v150, s64, v153
	ds_read_b128 v[178:181], v150
	ds_read_b128 v[182:185], v150 offset:1024
	ds_read_b128 v[186:189], v150 offset:2048
	ds_read_b128 v[190:193], v150 offset:3072
	s_add_i32 m0, s9, 0xc000
	ds_read_b128 v[194:197], v155
	ds_read_b128 v[198:201], v155 offset:1024
	ds_read_b128 v[202:205], v155 offset:2048
	ds_read_b128 v[206:209], v155 offset:3072
	ds_read_b128 v[218:221], v155 offset:4096
	ds_read_b128 v[222:225], v155 offset:5120
	ds_read_b128 v[226:229], v155 offset:6144
	ds_read_b128 v[230:233], v155 offset:7168
	global_load_lds_dwordx4 v144, s[0:1]
	s_add_i32 m0, s9, 0xe000
	s_nop 0
	global_load_lds_dwordx4 v142, s[0:1]
	s_cmp_eq_u32 s98, 16
	s_cbranch_scc1 .Lp1pk_w1_16
	s_cmp_eq_u32 s98, 8
	s_cbranch_scc1 .Lp1pk_w1_8
	s_waitcnt vmcnt(8)
	s_branch .Lp1pk_w1_done

.Lp1pk_w1_done:
	s_waitcnt lgkmcnt(0)
	s_barrier
	s_setprio 1
	s_waitcnt lgkmcnt(0)
	v_mfma_f32_16x16x32_bf16 v[70:73], v[146:149], v[194:197], 0
	v_mfma_f32_16x16x32_bf16 v[66:69], v[160:163], v[194:197], 0
	v_mfma_f32_16x16x32_bf16 v[62:65], v[146:149], v[202:205], 0
	v_mfma_f32_16x16x32_bf16 v[58:61], v[160:163], v[202:205], 0
	v_mfma_f32_16x16x32_bf16 v[50:53], v[146:149], v[218:221], 0
	v_mfma_f32_16x16x32_bf16 v[46:49], v[160:163], v[218:221], 0
	v_mfma_f32_16x16x32_bf16 v[42:45], v[146:149], v[226:229], 0
	v_mfma_f32_16x16x32_bf16 v[38:41], v[160:163], v[226:229], 0
	v_mfma_f32_16x16x32_bf16 v[70:73], v[156:159], v[198:201], v[70:73]
	v_mfma_f32_16x16x32_bf16 v[66:69], v[174:177], v[198:201], v[66:69]
	v_mfma_f32_16x16x32_bf16 v[62:65], v[156:159], v[206:209], v[62:65]
	v_mfma_f32_16x16x32_bf16 v[58:61], v[174:177], v[206:209], v[58:61]
	v_mfma_f32_16x16x32_bf16 v[50:53], v[156:159], v[222:225], v[50:53]
	v_mfma_f32_16x16x32_bf16 v[46:49], v[174:177], v[222:225], v[46:49]
	v_mfma_f32_16x16x32_bf16 v[42:45], v[156:159], v[230:233], v[42:45]
	v_mfma_f32_16x16x32_bf16 v[38:41], v[174:177], v[230:233], v[38:41]
	s_setprio 0
	s_setprio 1
	v_mfma_f32_16x16x32_bf16 v[126:129], v[178:181], v[194:197], 0
	v_mfma_f32_16x16x32_bf16 v[122:125], v[186:189], v[194:197], 0
	v_mfma_f32_16x16x32_bf16 v[118:121], v[178:181], v[202:205], 0
	v_mfma_f32_16x16x32_bf16 v[114:117], v[186:189], v[202:205], 0
	v_mfma_f32_16x16x32_bf16 v[110:113], v[178:181], v[218:221], 0
	v_mfma_f32_16x16x32_bf16 v[106:109], v[186:189], v[218:221], 0
	v_mfma_f32_16x16x32_bf16 v[102:105], v[178:181], v[226:229], 0
	v_mfma_f32_16x16x32_bf16 v[98:101], v[186:189], v[226:229], 0
	v_mfma_f32_16x16x32_bf16 v[126:129], v[182:185], v[198:201], v[126:129]
	v_mfma_f32_16x16x32_bf16 v[122:125], v[190:193], v[198:201], v[122:125]
	v_mfma_f32_16x16x32_bf16 v[118:121], v[182:185], v[206:209], v[118:121]
	v_mfma_f32_16x16x32_bf16 v[114:117], v[190:193], v[206:209], v[114:117]
	v_mfma_f32_16x16x32_bf16 v[110:113], v[182:185], v[222:225], v[110:113]
	v_mfma_f32_16x16x32_bf16 v[106:109], v[190:193], v[222:225], v[106:109]
	v_mfma_f32_16x16x32_bf16 v[102:105], v[182:185], v[230:233], v[102:105]
	v_mfma_f32_16x16x32_bf16 v[98:101], v[190:193], v[230:233], v[98:101]
	s_setprio 0
	s_barrier
	s_add_i32 s30, s63, s8
	s_mov_b32 m0, s30
	ds_read_b128 v[194:197], v155 offset:16384
	ds_read_b128 v[198:201], v155 offset:17408
	ds_read_b128 v[202:205], v155 offset:18432
	ds_read_b128 v[206:209], v155 offset:19456
	ds_read_b128 v[218:221], v155 offset:20480
	ds_read_b128 v[222:225], v155 offset:21504
	ds_read_b128 v[226:229], v155 offset:22528
	ds_read_b128 v[230:233], v155 offset:23552
	global_load_lds_dwordx4 v134, s[48:49]
	s_add_i32 m0, s30, 0x2000
	s_add_u32 s30, s48, 0x80000
	s_mov_b64 s[80:81], s[48:49]
	s_addc_u32 s31, s49, 0
	s_add_i32 s63, s64, s8
	global_load_lds_dwordx4 v130, s[48:49]
	s_mov_b32 m0, s63
	v_lshl_add_u64 v[170:171], s[50:51], 0, v[132:133]
	global_load_lds_dwordx4 v134, s[30:31]
	s_add_i32 m0, s63, 0x2000
	s_nop 0
	global_load_lds_dwordx4 v130, s[30:31]
	s_mov_b32 m0, s9
	s_nop 0
	global_load_lds_dwordx4 v136, s[50:51]
	s_mov_b32 m0, s28
	s_nop 0
	global_load_lds_dwordx4 v132, s[50:51]
	s_cmp_eq_u32 s98, 16
	s_cbranch_scc1 .Lp1pk_w2_16
	s_cmp_eq_u32 s98, 8
	s_cbranch_scc1 .Lp1pk_w2_8
	s_waitcnt vmcnt(8)
	s_branch .Lp1pk_w2_done

.Lp1pk_w2_done:
	s_waitcnt lgkmcnt(0)
	s_barrier
	s_setprio 1
	s_waitcnt lgkmcnt(0)
	v_mfma_f32_16x16x32_bf16 v[30:33], v[146:149], v[194:197], 0
	v_mfma_f32_16x16x32_bf16 v[26:29], v[160:163], v[194:197], 0
	v_mfma_f32_16x16x32_bf16 v[22:25], v[146:149], v[202:205], 0
	v_mfma_f32_16x16x32_bf16 v[18:21], v[160:163], v[202:205], 0
	v_mfma_f32_16x16x32_bf16 v[14:17], v[146:149], v[218:221], 0
	v_mfma_f32_16x16x32_bf16 v[10:13], v[160:163], v[218:221], 0
	v_mfma_f32_16x16x32_bf16 v[6:9], v[146:149], v[226:229], 0
	v_mfma_f32_16x16x32_bf16 v[2:5], v[160:163], v[226:229], 0
	v_mfma_f32_16x16x32_bf16 v[30:33], v[156:159], v[198:201], v[30:33]
	v_mfma_f32_16x16x32_bf16 v[26:29], v[174:177], v[198:201], v[26:29]
	v_mfma_f32_16x16x32_bf16 v[22:25], v[156:159], v[206:209], v[22:25]
	v_mfma_f32_16x16x32_bf16 v[18:21], v[174:177], v[206:209], v[18:21]
	v_mfma_f32_16x16x32_bf16 v[14:17], v[156:159], v[222:225], v[14:17]
	v_mfma_f32_16x16x32_bf16 v[10:13], v[174:177], v[222:225], v[10:13]
	v_mfma_f32_16x16x32_bf16 v[6:9], v[156:159], v[230:233], v[6:9]
	v_mfma_f32_16x16x32_bf16 v[2:5], v[174:177], v[230:233], v[2:5]
	s_setprio 0
	s_setprio 1
	v_mfma_f32_16x16x32_bf16 v[94:97], v[178:181], v[194:197], 0
	v_mfma_f32_16x16x32_bf16 v[90:93], v[186:189], v[194:197], 0
	v_mfma_f32_16x16x32_bf16 v[86:89], v[178:181], v[202:205], 0
	v_mfma_f32_16x16x32_bf16 v[82:85], v[186:189], v[202:205], 0
	v_mfma_f32_16x16x32_bf16 v[78:81], v[178:181], v[218:221], 0
	v_mfma_f32_16x16x32_bf16 v[74:77], v[186:189], v[218:221], 0
	v_mfma_f32_16x16x32_bf16 v[54:57], v[178:181], v[226:229], 0
	v_mfma_f32_16x16x32_bf16 v[34:37], v[186:189], v[226:229], 0
	v_mfma_f32_16x16x32_bf16 v[94:97], v[182:185], v[198:201], v[94:97]
	v_mfma_f32_16x16x32_bf16 v[90:93], v[190:193], v[198:201], v[90:93]
	v_mfma_f32_16x16x32_bf16 v[86:89], v[182:185], v[206:209], v[86:89]
	v_mfma_f32_16x16x32_bf16 v[82:85], v[190:193], v[206:209], v[82:85]
	v_mfma_f32_16x16x32_bf16 v[78:81], v[182:185], v[222:225], v[78:81]
	v_mfma_f32_16x16x32_bf16 v[74:77], v[190:193], v[222:225], v[74:77]
	v_mfma_f32_16x16x32_bf16 v[54:57], v[182:185], v[230:233], v[54:57]
	v_mfma_f32_16x16x32_bf16 v[34:37], v[190:193], v[230:233], v[34:37]
	s_setprio 0
	s_barrier
	s_add_i32 s63, 0, 0x18000
	v_add_u32_e32 v172, s63, v153
	s_add_i32 s64, 0, 0x1c000
	ds_read_b128 v[146:149], v172
	ds_read_b128 v[156:159], v172 offset:1024
	ds_read_b128 v[160:163], v172 offset:2048
	ds_read_b128 v[174:177], v172 offset:3072
	v_add_u32_e32 v172, s64, v153
	ds_read_b128 v[178:181], v172
	ds_read_b128 v[182:185], v172 offset:1024
	ds_read_b128 v[186:189], v172 offset:2048
	ds_read_b128 v[190:193], v172 offset:3072
	s_add_u32 s30, s50, 0x80000
	s_addc_u32 s31, s51, 0
	s_mov_b32 m0, s29
	ds_read_b128 v[194:197], v155 offset:32768
	ds_read_b128 v[198:201], v155 offset:33792
	ds_read_b128 v[202:205], v155 offset:34816
	ds_read_b128 v[206:209], v155 offset:35840
	ds_read_b128 v[218:221], v155 offset:36864
	ds_read_b128 v[222:225], v155 offset:37888
	ds_read_b128 v[226:229], v155 offset:38912
	ds_read_b128 v[230:233], v155 offset:39936
	global_load_lds_dwordx4 v136, s[30:31]
	v_lshl_add_u64 v[172:173], s[30:31], 0, v[132:133]
	s_mov_b32 m0, s35
	s_nop 0
	global_load_lds_dwordx4 v132, s[30:31]
	s_waitcnt vmcnt(8)
	s_waitcnt lgkmcnt(0)
	s_barrier
	s_setprio 1
	s_waitcnt lgkmcnt(0)
	v_mfma_f32_16x16x32_bf16 v[70:73], v[146:149], v[194:197], v[70:73]
	v_mfma_f32_16x16x32_bf16 v[66:69], v[160:163], v[194:197], v[66:69]
	v_mfma_f32_16x16x32_bf16 v[62:65], v[146:149], v[202:205], v[62:65]
	v_mfma_f32_16x16x32_bf16 v[58:61], v[160:163], v[202:205], v[58:61]
	v_mfma_f32_16x16x32_bf16 v[50:53], v[146:149], v[218:221], v[50:53]
	v_mfma_f32_16x16x32_bf16 v[46:49], v[160:163], v[218:221], v[46:49]
	v_mfma_f32_16x16x32_bf16 v[42:45], v[146:149], v[226:229], v[42:45]
	v_mfma_f32_16x16x32_bf16 v[38:41], v[160:163], v[226:229], v[38:41]
	v_mfma_f32_16x16x32_bf16 v[70:73], v[156:159], v[198:201], v[70:73]
	v_mfma_f32_16x16x32_bf16 v[66:69], v[174:177], v[198:201], v[66:69]
	v_mfma_f32_16x16x32_bf16 v[62:65], v[156:159], v[206:209], v[62:65]
	v_mfma_f32_16x16x32_bf16 v[58:61], v[174:177], v[206:209], v[58:61]
	v_mfma_f32_16x16x32_bf16 v[50:53], v[156:159], v[222:225], v[50:53]
	v_mfma_f32_16x16x32_bf16 v[46:49], v[174:177], v[222:225], v[46:49]
	v_mfma_f32_16x16x32_bf16 v[42:45], v[156:159], v[230:233], v[42:45]
	v_mfma_f32_16x16x32_bf16 v[38:41], v[174:177], v[230:233], v[38:41]
	s_setprio 0
	s_setprio 1
	v_mfma_f32_16x16x32_bf16 v[126:129], v[178:181], v[194:197], v[126:129]
	v_mfma_f32_16x16x32_bf16 v[122:125], v[186:189], v[194:197], v[122:125]
	v_mfma_f32_16x16x32_bf16 v[118:121], v[178:181], v[202:205], v[118:121]
	v_mfma_f32_16x16x32_bf16 v[114:117], v[186:189], v[202:205], v[114:117]
	v_mfma_f32_16x16x32_bf16 v[110:113], v[178:181], v[218:221], v[110:113]
	v_mfma_f32_16x16x32_bf16 v[106:109], v[186:189], v[218:221], v[106:109]
	v_mfma_f32_16x16x32_bf16 v[102:105], v[178:181], v[226:229], v[102:105]
	v_mfma_f32_16x16x32_bf16 v[98:101], v[186:189], v[226:229], v[98:101]
	v_mfma_f32_16x16x32_bf16 v[126:129], v[182:185], v[198:201], v[126:129]
	v_mfma_f32_16x16x32_bf16 v[122:125], v[190:193], v[198:201], v[122:125]
	v_mfma_f32_16x16x32_bf16 v[118:121], v[182:185], v[206:209], v[118:121]
	v_mfma_f32_16x16x32_bf16 v[114:117], v[190:193], v[206:209], v[114:117]
	v_mfma_f32_16x16x32_bf16 v[110:113], v[182:185], v[222:225], v[110:113]
	v_mfma_f32_16x16x32_bf16 v[106:109], v[190:193], v[222:225], v[106:109]
	v_mfma_f32_16x16x32_bf16 v[102:105], v[182:185], v[230:233], v[102:105]
	v_mfma_f32_16x16x32_bf16 v[98:101], v[190:193], v[230:233], v[98:101]
	s_setprio 0
	s_barrier
	s_add_i32 s30, s63, s8
	s_add_i32 m0, s30, 0xffffff80
	ds_read_b128 v[194:197], v155 offset:49152
	ds_read_b128 v[198:201], v155 offset:50176
	ds_read_b128 v[202:205], v155 offset:51200
	ds_read_b128 v[206:209], v155 offset:52224
	ds_read_b128 v[218:221], v155 offset:53248
	ds_read_b128 v[222:225], v155 offset:54272
	ds_read_b128 v[226:229], v155 offset:55296
	ds_read_b128 v[230:233], v155 offset:56320
	global_load_lds_dwordx4 v134, s[48:49] offset:128
	s_add_i32 m0, s30, 0x1f80
	s_add_u32 s30, s48, 0x80080
	s_addc_u32 s31, s49, 0
	s_add_i32 s48, s64, s8
	global_load_lds_dwordx4 v130, s[80:81] offset:128
	s_mov_b32 m0, s48
	s_nop 0
	global_load_lds_dwordx4 v134, s[30:31]
	s_add_i32 m0, s48, 0x2000
	s_nop 0
	global_load_lds_dwordx4 v130, s[30:31]
	s_add_i32 m0, s52, 0xffffff80
	s_nop 0
	global_load_lds_dwordx4 v136, s[50:51] offset:128
	v_lshl_add_u64 v[150:151], v[170:171], 0, s[24:25]
	s_add_i32 m0, s53, 0xffffff80
	s_nop 0
	global_load_lds_dwordx4 v132, s[50:51] offset:128
	s_waitcnt vmcnt(8)
	s_waitcnt lgkmcnt(0)
	s_barrier
	s_setprio 1
	s_waitcnt lgkmcnt(0)
	v_mfma_f32_16x16x32_bf16 v[30:33], v[146:149], v[194:197], v[30:33]
	v_mfma_f32_16x16x32_bf16 v[26:29], v[160:163], v[194:197], v[26:29]
	v_mfma_f32_16x16x32_bf16 v[22:25], v[146:149], v[202:205], v[22:25]
	v_mfma_f32_16x16x32_bf16 v[18:21], v[160:163], v[202:205], v[18:21]
	v_mfma_f32_16x16x32_bf16 v[14:17], v[146:149], v[218:221], v[14:17]
	v_mfma_f32_16x16x32_bf16 v[10:13], v[160:163], v[218:221], v[10:13]
	v_mfma_f32_16x16x32_bf16 v[6:9], v[146:149], v[226:229], v[6:9]
	v_mfma_f32_16x16x32_bf16 v[2:5], v[160:163], v[226:229], v[2:5]
	v_mfma_f32_16x16x32_bf16 v[30:33], v[156:159], v[198:201], v[30:33]
	v_mfma_f32_16x16x32_bf16 v[26:29], v[174:177], v[198:201], v[26:29]
	v_mfma_f32_16x16x32_bf16 v[22:25], v[156:159], v[206:209], v[22:25]
	v_mfma_f32_16x16x32_bf16 v[18:21], v[174:177], v[206:209], v[18:21]
	v_mfma_f32_16x16x32_bf16 v[14:17], v[156:159], v[222:225], v[14:17]
	v_mfma_f32_16x16x32_bf16 v[10:13], v[174:177], v[222:225], v[10:13]
	v_mfma_f32_16x16x32_bf16 v[6:9], v[156:159], v[230:233], v[6:9]
	v_mfma_f32_16x16x32_bf16 v[2:5], v[174:177], v[230:233], v[2:5]
	s_setprio 0
	s_setprio 1
	v_mfma_f32_16x16x32_bf16 v[94:97], v[178:181], v[194:197], v[94:97]
	v_mfma_f32_16x16x32_bf16 v[90:93], v[186:189], v[194:197], v[90:93]
	v_mfma_f32_16x16x32_bf16 v[86:89], v[178:181], v[202:205], v[86:89]
	v_mfma_f32_16x16x32_bf16 v[82:85], v[186:189], v[202:205], v[82:85]
	v_mfma_f32_16x16x32_bf16 v[78:81], v[178:181], v[218:221], v[78:81]
	v_mfma_f32_16x16x32_bf16 v[74:77], v[186:189], v[218:221], v[74:77]
	v_mfma_f32_16x16x32_bf16 v[54:57], v[178:181], v[226:229], v[54:57]
	v_mfma_f32_16x16x32_bf16 v[34:37], v[186:189], v[226:229], v[34:37]
	v_mfma_f32_16x16x32_bf16 v[94:97], v[182:185], v[198:201], v[94:97]
	v_mfma_f32_16x16x32_bf16 v[90:93], v[190:193], v[198:201], v[90:93]
	v_mfma_f32_16x16x32_bf16 v[86:89], v[182:185], v[206:209], v[86:89]
	v_mfma_f32_16x16x32_bf16 v[82:85], v[190:193], v[206:209], v[82:85]
	v_mfma_f32_16x16x32_bf16 v[78:81], v[182:185], v[222:225], v[78:81]
	v_mfma_f32_16x16x32_bf16 v[74:77], v[190:193], v[222:225], v[74:77]
	v_mfma_f32_16x16x32_bf16 v[54:57], v[182:185], v[230:233], v[54:57]
	v_mfma_f32_16x16x32_bf16 v[34:37], v[190:193], v[230:233], v[34:37]
	s_setprio 0
	s_barrier
	s_add_i32 s62, s62, 2
	s_add_u32 s60, s60, 0x100
	s_addc_u32 s61, s61, 0
	s_add_u32 s0, s0, 0x100
	s_addc_u32 s1, s1, 0
	s_cmp_gt_u32 s62, 29
.LBB0_105:
	s_add_u32 s30, s0, 0xfff80080
	s_addc_u32 s31, s1, -1
	s_add_i32 s63, 0, 0x10000
	s_cmp_eq_u32 s62, 28
	s_cselect_b32 s51, s41, s31
	s_cselect_b32 s50, s47, s30
	v_add_u32_e32 v150, s63, v153
	s_cselect_b32 s49, s39, s61
	s_cselect_b32 s48, s55, s60
	s_add_i32 s64, 0, 0x14000
	ds_read_b128 v[146:149], v150
	ds_read_b128 v[156:159], v150 offset:1024
	ds_read_b128 v[160:163], v150 offset:2048
	ds_read_b128 v[174:177], v150 offset:3072
	v_add_u32_e32 v150, s64, v153
	ds_read_b128 v[178:181], v150
	ds_read_b128 v[182:185], v150 offset:1024
	ds_read_b128 v[186:189], v150 offset:2048
	ds_read_b128 v[190:193], v150 offset:3072
	s_add_i32 m0, s9, 0xc000
	ds_read_b128 v[194:197], v155
	ds_read_b128 v[198:201], v155 offset:1024
	ds_read_b128 v[202:205], v155 offset:2048
	ds_read_b128 v[206:209], v155 offset:3072
	ds_read_b128 v[218:221], v155 offset:4096
	ds_read_b128 v[222:225], v155 offset:5120
	ds_read_b128 v[226:229], v155 offset:6144
	ds_read_b128 v[230:233], v155 offset:7168
	global_load_lds_dwordx4 v144, s[0:1]
	s_add_i32 m0, s9, 0xe000
	s_nop 0
	global_load_lds_dwordx4 v142, s[0:1]
	s_waitcnt vmcnt(8)
	s_waitcnt lgkmcnt(0)
	s_barrier
	s_setprio 1
	s_waitcnt lgkmcnt(0)
	v_mfma_f32_16x16x32_bf16 v[70:73], v[146:149], v[194:197], v[70:73]
	v_mfma_f32_16x16x32_bf16 v[66:69], v[160:163], v[194:197], v[66:69]
	v_mfma_f32_16x16x32_bf16 v[62:65], v[146:149], v[202:205], v[62:65]
	v_mfma_f32_16x16x32_bf16 v[58:61], v[160:163], v[202:205], v[58:61]
	v_mfma_f32_16x16x32_bf16 v[50:53], v[146:149], v[218:221], v[50:53]
	v_mfma_f32_16x16x32_bf16 v[46:49], v[160:163], v[218:221], v[46:49]
	v_mfma_f32_16x16x32_bf16 v[42:45], v[146:149], v[226:229], v[42:45]
	v_mfma_f32_16x16x32_bf16 v[38:41], v[160:163], v[226:229], v[38:41]
	v_mfma_f32_16x16x32_bf16 v[70:73], v[156:159], v[198:201], v[70:73]
	v_mfma_f32_16x16x32_bf16 v[66:69], v[174:177], v[198:201], v[66:69]
	v_mfma_f32_16x16x32_bf16 v[62:65], v[156:159], v[206:209], v[62:65]
	v_mfma_f32_16x16x32_bf16 v[58:61], v[174:177], v[206:209], v[58:61]
	v_mfma_f32_16x16x32_bf16 v[50:53], v[156:159], v[222:225], v[50:53]
	v_mfma_f32_16x16x32_bf16 v[46:49], v[174:177], v[222:225], v[46:49]
	v_mfma_f32_16x16x32_bf16 v[42:45], v[156:159], v[230:233], v[42:45]
	v_mfma_f32_16x16x32_bf16 v[38:41], v[174:177], v[230:233], v[38:41]
	s_setprio 0
	s_setprio 1
	v_mfma_f32_16x16x32_bf16 v[126:129], v[178:181], v[194:197], v[126:129]
	v_mfma_f32_16x16x32_bf16 v[122:125], v[186:189], v[194:197], v[122:125]
	v_mfma_f32_16x16x32_bf16 v[118:121], v[178:181], v[202:205], v[118:121]
	v_mfma_f32_16x16x32_bf16 v[114:117], v[186:189], v[202:205], v[114:117]
	v_mfma_f32_16x16x32_bf16 v[110:113], v[178:181], v[218:221], v[110:113]
	v_mfma_f32_16x16x32_bf16 v[106:109], v[186:189], v[218:221], v[106:109]
	v_mfma_f32_16x16x32_bf16 v[102:105], v[178:181], v[226:229], v[102:105]
	v_mfma_f32_16x16x32_bf16 v[98:101], v[186:189], v[226:229], v[98:101]
	v_mfma_f32_16x16x32_bf16 v[126:129], v[182:185], v[198:201], v[126:129]
	v_mfma_f32_16x16x32_bf16 v[122:125], v[190:193], v[198:201], v[122:125]
	v_mfma_f32_16x16x32_bf16 v[118:121], v[182:185], v[206:209], v[118:121]
	v_mfma_f32_16x16x32_bf16 v[114:117], v[190:193], v[206:209], v[114:117]
	v_mfma_f32_16x16x32_bf16 v[110:113], v[182:185], v[222:225], v[110:113]
	v_mfma_f32_16x16x32_bf16 v[106:109], v[190:193], v[222:225], v[106:109]
	v_mfma_f32_16x16x32_bf16 v[102:105], v[182:185], v[230:233], v[102:105]
	v_mfma_f32_16x16x32_bf16 v[98:101], v[190:193], v[230:233], v[98:101]
	s_setprio 0
	s_barrier
	s_add_i32 s30, s63, s8
	s_mov_b32 m0, s30
	ds_read_b128 v[194:197], v155 offset:16384
	ds_read_b128 v[198:201], v155 offset:17408
	ds_read_b128 v[202:205], v155 offset:18432
	ds_read_b128 v[206:209], v155 offset:19456
	ds_read_b128 v[218:221], v155 offset:20480
	ds_read_b128 v[222:225], v155 offset:21504
	ds_read_b128 v[226:229], v155 offset:22528
	ds_read_b128 v[230:233], v155 offset:23552
	global_load_lds_dwordx4 v134, s[48:49]
	s_add_i32 m0, s30, 0x2000
	s_add_u32 s30, s48, 0x80000
	s_mov_b64 s[82:83], s[48:49]
	s_addc_u32 s31, s49, 0
	s_add_i32 s63, s64, s8
	global_load_lds_dwordx4 v130, s[48:49]
	s_mov_b32 m0, s63
	s_nop 0
	global_load_lds_dwordx4 v134, s[30:31]
	s_add_i32 m0, s63, 0x2000
	s_nop 0
	global_load_lds_dwordx4 v130, s[30:31]
	s_mov_b32 m0, s9
	s_nop 0
	global_load_lds_dwordx4 v136, s[50:51]
	s_mov_b32 m0, s28
	s_nop 0
	global_load_lds_dwordx4 v132, s[50:51]
	s_waitcnt vmcnt(8)
	s_waitcnt lgkmcnt(0)
	s_barrier
	s_setprio 1
	s_waitcnt lgkmcnt(0)
	v_mfma_f32_16x16x32_bf16 v[30:33], v[146:149], v[194:197], v[30:33]
	v_mfma_f32_16x16x32_bf16 v[26:29], v[160:163], v[194:197], v[26:29]
	v_mfma_f32_16x16x32_bf16 v[22:25], v[146:149], v[202:205], v[22:25]
	v_mfma_f32_16x16x32_bf16 v[18:21], v[160:163], v[202:205], v[18:21]
	v_mfma_f32_16x16x32_bf16 v[14:17], v[146:149], v[218:221], v[14:17]
	v_mfma_f32_16x16x32_bf16 v[10:13], v[160:163], v[218:221], v[10:13]
	v_mfma_f32_16x16x32_bf16 v[6:9], v[146:149], v[226:229], v[6:9]
	v_mfma_f32_16x16x32_bf16 v[2:5], v[160:163], v[226:229], v[2:5]
	v_mfma_f32_16x16x32_bf16 v[30:33], v[156:159], v[198:201], v[30:33]
	v_mfma_f32_16x16x32_bf16 v[26:29], v[174:177], v[198:201], v[26:29]
	v_mfma_f32_16x16x32_bf16 v[22:25], v[156:159], v[206:209], v[22:25]
	v_mfma_f32_16x16x32_bf16 v[18:21], v[174:177], v[206:209], v[18:21]
	v_mfma_f32_16x16x32_bf16 v[14:17], v[156:159], v[222:225], v[14:17]
	v_mfma_f32_16x16x32_bf16 v[10:13], v[174:177], v[222:225], v[10:13]
	v_mfma_f32_16x16x32_bf16 v[6:9], v[156:159], v[230:233], v[6:9]
	v_mfma_f32_16x16x32_bf16 v[2:5], v[174:177], v[230:233], v[2:5]
	s_setprio 0
	s_setprio 1
	v_mfma_f32_16x16x32_bf16 v[94:97], v[178:181], v[194:197], v[94:97]
	v_mfma_f32_16x16x32_bf16 v[90:93], v[186:189], v[194:197], v[90:93]
	v_mfma_f32_16x16x32_bf16 v[86:89], v[178:181], v[202:205], v[86:89]
	v_mfma_f32_16x16x32_bf16 v[82:85], v[186:189], v[202:205], v[82:85]
	v_mfma_f32_16x16x32_bf16 v[78:81], v[178:181], v[218:221], v[78:81]
	v_mfma_f32_16x16x32_bf16 v[74:77], v[186:189], v[218:221], v[74:77]
	v_mfma_f32_16x16x32_bf16 v[54:57], v[178:181], v[226:229], v[54:57]
	v_mfma_f32_16x16x32_bf16 v[34:37], v[186:189], v[226:229], v[34:37]
	v_mfma_f32_16x16x32_bf16 v[94:97], v[182:185], v[198:201], v[94:97]
	v_mfma_f32_16x16x32_bf16 v[90:93], v[190:193], v[198:201], v[90:93]
	v_mfma_f32_16x16x32_bf16 v[86:89], v[182:185], v[206:209], v[86:89]
	v_mfma_f32_16x16x32_bf16 v[82:85], v[190:193], v[206:209], v[82:85]
	v_mfma_f32_16x16x32_bf16 v[78:81], v[182:185], v[222:225], v[78:81]
	v_mfma_f32_16x16x32_bf16 v[74:77], v[190:193], v[222:225], v[74:77]
	v_mfma_f32_16x16x32_bf16 v[54:57], v[182:185], v[230:233], v[54:57]
	v_mfma_f32_16x16x32_bf16 v[34:37], v[190:193], v[230:233], v[34:37]
	s_setprio 0
	s_barrier
	s_add_i32 s63, 0, 0x18000
	v_add_u32_e32 v172, s63, v153
	s_add_i32 s64, 0, 0x1c000
	ds_read_b128 v[146:149], v172
	ds_read_b128 v[156:159], v172 offset:1024
	ds_read_b128 v[160:163], v172 offset:2048
	ds_read_b128 v[174:177], v172 offset:3072
	v_add_u32_e32 v172, s64, v153
	ds_read_b128 v[178:181], v172
	ds_read_b128 v[182:185], v172 offset:1024
	ds_read_b128 v[186:189], v172 offset:2048
	ds_read_b128 v[190:193], v172 offset:3072
	s_add_u32 s30, s50, 0x80000
	s_addc_u32 s31, s51, 0
	s_mov_b32 m0, s29
	ds_read_b128 v[194:197], v155 offset:32768
	ds_read_b128 v[198:201], v155 offset:33792
	ds_read_b128 v[202:205], v155 offset:34816
	ds_read_b128 v[206:209], v155 offset:35840
	ds_read_b128 v[218:221], v155 offset:36864
	ds_read_b128 v[222:225], v155 offset:37888
	ds_read_b128 v[226:229], v155 offset:38912
	ds_read_b128 v[230:233], v155 offset:39936
	global_load_lds_dwordx4 v136, s[30:31]
	s_mov_b32 m0, s35
	s_nop 0
	global_load_lds_dwordx4 v132, s[30:31]
	s_waitcnt vmcnt(8)
	s_waitcnt lgkmcnt(0)
	s_barrier
	s_setprio 1
	s_waitcnt lgkmcnt(0)
	v_mfma_f32_16x16x32_bf16 v[70:73], v[146:149], v[194:197], v[70:73]
	v_mfma_f32_16x16x32_bf16 v[66:69], v[160:163], v[194:197], v[66:69]
	v_mfma_f32_16x16x32_bf16 v[62:65], v[146:149], v[202:205], v[62:65]
	v_mfma_f32_16x16x32_bf16 v[58:61], v[160:163], v[202:205], v[58:61]
	v_mfma_f32_16x16x32_bf16 v[50:53], v[146:149], v[218:221], v[50:53]
	v_mfma_f32_16x16x32_bf16 v[46:49], v[160:163], v[218:221], v[46:49]
	v_mfma_f32_16x16x32_bf16 v[42:45], v[146:149], v[226:229], v[42:45]
	v_mfma_f32_16x16x32_bf16 v[38:41], v[160:163], v[226:229], v[38:41]
	v_mfma_f32_16x16x32_bf16 v[70:73], v[156:159], v[198:201], v[70:73]
	v_mfma_f32_16x16x32_bf16 v[66:69], v[174:177], v[198:201], v[66:69]
	v_mfma_f32_16x16x32_bf16 v[62:65], v[156:159], v[206:209], v[62:65]
	v_mfma_f32_16x16x32_bf16 v[58:61], v[174:177], v[206:209], v[58:61]
	v_mfma_f32_16x16x32_bf16 v[50:53], v[156:159], v[222:225], v[50:53]
	v_mfma_f32_16x16x32_bf16 v[46:49], v[174:177], v[222:225], v[46:49]
	v_mfma_f32_16x16x32_bf16 v[42:45], v[156:159], v[230:233], v[42:45]
	v_mfma_f32_16x16x32_bf16 v[38:41], v[174:177], v[230:233], v[38:41]
	s_setprio 0
	s_setprio 1
	v_mfma_f32_16x16x32_bf16 v[126:129], v[178:181], v[194:197], v[126:129]
	v_mfma_f32_16x16x32_bf16 v[122:125], v[186:189], v[194:197], v[122:125]
	v_mfma_f32_16x16x32_bf16 v[118:121], v[178:181], v[202:205], v[118:121]
	v_mfma_f32_16x16x32_bf16 v[114:117], v[186:189], v[202:205], v[114:117]
	v_mfma_f32_16x16x32_bf16 v[110:113], v[178:181], v[218:221], v[110:113]
	v_mfma_f32_16x16x32_bf16 v[106:109], v[186:189], v[218:221], v[106:109]
	v_mfma_f32_16x16x32_bf16 v[102:105], v[178:181], v[226:229], v[102:105]
	v_mfma_f32_16x16x32_bf16 v[98:101], v[186:189], v[226:229], v[98:101]
	v_mfma_f32_16x16x32_bf16 v[126:129], v[182:185], v[198:201], v[126:129]
	v_mfma_f32_16x16x32_bf16 v[122:125], v[190:193], v[198:201], v[122:125]
	v_mfma_f32_16x16x32_bf16 v[118:121], v[182:185], v[206:209], v[118:121]
	v_mfma_f32_16x16x32_bf16 v[114:117], v[190:193], v[206:209], v[114:117]
	v_mfma_f32_16x16x32_bf16 v[110:113], v[182:185], v[222:225], v[110:113]
	v_mfma_f32_16x16x32_bf16 v[106:109], v[190:193], v[222:225], v[106:109]
	v_mfma_f32_16x16x32_bf16 v[102:105], v[182:185], v[230:233], v[102:105]
	v_mfma_f32_16x16x32_bf16 v[98:101], v[190:193], v[230:233], v[98:101]
	s_setprio 0
	s_barrier
	s_add_i32 s30, s63, s8
	s_add_i32 m0, s30, 0xffffff80
	ds_read_b128 v[194:197], v155 offset:49152
	ds_read_b128 v[198:201], v155 offset:50176
	ds_read_b128 v[202:205], v155 offset:51200
	ds_read_b128 v[206:209], v155 offset:52224
	ds_read_b128 v[218:221], v155 offset:53248
	ds_read_b128 v[222:225], v155 offset:54272
	ds_read_b128 v[226:229], v155 offset:55296
	ds_read_b128 v[230:233], v155 offset:56320
	global_load_lds_dwordx4 v134, s[48:49] offset:128
	s_add_i32 m0, s30, 0x1f80
	s_add_u32 s30, s48, 0x80080
	s_addc_u32 s31, s49, 0
	s_add_i32 s48, s64, s8
	global_load_lds_dwordx4 v130, s[82:83] offset:128
	s_mov_b32 m0, s48
	s_nop 0
	global_load_lds_dwordx4 v134, s[30:31]
	s_add_i32 m0, s48, 0x2000
	s_nop 0
	global_load_lds_dwordx4 v130, s[30:31]
	s_add_i32 m0, s52, 0xffffff80
	s_nop 0
	global_load_lds_dwordx4 v136, s[50:51] offset:128
	s_add_i32 m0, s53, 0xffffff80
	s_nop 0
	global_load_lds_dwordx4 v132, s[50:51] offset:128
	s_waitcnt vmcnt(8)
	s_waitcnt lgkmcnt(0)
	s_barrier
	s_setprio 1
	s_waitcnt lgkmcnt(0)
	v_mfma_f32_16x16x32_bf16 v[30:33], v[146:149], v[194:197], v[30:33]
	v_mfma_f32_16x16x32_bf16 v[26:29], v[160:163], v[194:197], v[26:29]
	v_mfma_f32_16x16x32_bf16 v[22:25], v[146:149], v[202:205], v[22:25]
	v_mfma_f32_16x16x32_bf16 v[18:21], v[160:163], v[202:205], v[18:21]
	v_mfma_f32_16x16x32_bf16 v[14:17], v[146:149], v[218:221], v[14:17]
	v_mfma_f32_16x16x32_bf16 v[10:13], v[160:163], v[218:221], v[10:13]
	v_mfma_f32_16x16x32_bf16 v[6:9], v[146:149], v[226:229], v[6:9]
	v_mfma_f32_16x16x32_bf16 v[2:5], v[160:163], v[226:229], v[2:5]
	v_mfma_f32_16x16x32_bf16 v[30:33], v[156:159], v[198:201], v[30:33]
	v_mfma_f32_16x16x32_bf16 v[26:29], v[174:177], v[198:201], v[26:29]
	v_mfma_f32_16x16x32_bf16 v[22:25], v[156:159], v[206:209], v[22:25]
	v_mfma_f32_16x16x32_bf16 v[18:21], v[174:177], v[206:209], v[18:21]
	v_mfma_f32_16x16x32_bf16 v[14:17], v[156:159], v[222:225], v[14:17]
	v_mfma_f32_16x16x32_bf16 v[10:13], v[174:177], v[222:225], v[10:13]
	v_mfma_f32_16x16x32_bf16 v[6:9], v[156:159], v[230:233], v[6:9]
	v_mfma_f32_16x16x32_bf16 v[2:5], v[174:177], v[230:233], v[2:5]
	s_setprio 0
	s_setprio 1
	v_mfma_f32_16x16x32_bf16 v[94:97], v[178:181], v[194:197], v[94:97]
	v_mfma_f32_16x16x32_bf16 v[90:93], v[186:189], v[194:197], v[90:93]
	v_mfma_f32_16x16x32_bf16 v[86:89], v[178:181], v[202:205], v[86:89]
	v_mfma_f32_16x16x32_bf16 v[82:85], v[186:189], v[202:205], v[82:85]
	v_mfma_f32_16x16x32_bf16 v[78:81], v[178:181], v[218:221], v[78:81]
	v_mfma_f32_16x16x32_bf16 v[74:77], v[186:189], v[218:221], v[74:77]
	v_mfma_f32_16x16x32_bf16 v[54:57], v[178:181], v[226:229], v[54:57]
	v_mfma_f32_16x16x32_bf16 v[34:37], v[186:189], v[226:229], v[34:37]
	v_mfma_f32_16x16x32_bf16 v[94:97], v[182:185], v[198:201], v[94:97]
	v_mfma_f32_16x16x32_bf16 v[90:93], v[190:193], v[198:201], v[90:93]
	v_mfma_f32_16x16x32_bf16 v[86:89], v[182:185], v[206:209], v[86:89]
	v_mfma_f32_16x16x32_bf16 v[82:85], v[190:193], v[206:209], v[82:85]
	v_mfma_f32_16x16x32_bf16 v[78:81], v[182:185], v[222:225], v[78:81]
	v_mfma_f32_16x16x32_bf16 v[74:77], v[190:193], v[222:225], v[74:77]
	v_mfma_f32_16x16x32_bf16 v[54:57], v[182:185], v[230:233], v[54:57]
	v_mfma_f32_16x16x32_bf16 v[34:37], v[190:193], v[230:233], v[34:37]
	s_setprio 0
	s_barrier
	s_add_i32 s62, s62, 2
	s_add_u32 s60, s60, 0x100
	s_addc_u32 s61, s61, 0
	s_add_u32 s0, s0, 0x100
	s_addc_u32 s1, s1, 0
	s_cmp_gt_u32 s62, 29
	s_cbranch_scc0 .LBB0_105
	s_and_b64 vcc, exec, s[16:17]
	s_cbranch_vccz .LBB0_108
	s_barrier
